# write-through (sc1) also on the GLA scan's output stores (the data still dirty in L2 at the P2->P3 grid barrier)
# baseline (speedup 1.0000x reference)
.LBB0_222:
	s_or_b64 exec, exec, s[28:29]
	ds_write_b128 v121, v[10:13]
	ds_write_b128 v111, v[14:17] offset:36864
	s_waitcnt lgkmcnt(0)
	s_barrier
	ds_read_b128 v[10:13], v95 offset:64512
	ds_read_b128 v[14:17], v125
	ds_read_b128 v[18:21], v125 offset:64
	ds_read_b128 v[22:25], v95 offset:64576
	ds_read_b128 v[26:29], v102 offset:2304
	ds_read_b128 v[30:33], v102 offset:2368
	s_waitcnt lgkmcnt(4)
	v_mfma_f32_16x16x32_bf16 v[10:13], v[10:13], v[14:17], 0
	ds_read_b128 v[34:37], v95 offset:27648
	ds_read_b128 v[38:41], v95 offset:27712
	s_add_i32 s42, s42, s3
	s_cmpk_lt_i32 s42, 0x100
	s_waitcnt lgkmcnt(3)
	v_mfma_f32_16x16x32_bf16 v[26:29], v[26:29], v[14:17], 0
	v_mfma_f32_16x16x32_bf16 v[10:13], v[22:25], v[18:21], v[10:13]
	s_waitcnt lgkmcnt(2)
	v_mfma_f32_16x16x32_bf16 v[22:25], v[30:33], v[18:21], v[26:29]
	s_nop 4
	ds_read_b128 v[26:29], v95 offset:29952
	ds_read_b128 v[30:33], v95 offset:30016
	v_pk_mul_f32 v[12:13], v[60:61], v[12:13]
	v_pk_mul_f32 v[10:11], v[58:59], v[10:11]
	v_pk_mul_f32 v[24:25], v[64:65], v[24:25]
	v_pk_mul_f32 v[22:23], v[62:63], v[22:23]
	v_cvt_pk_bf16_f32 v10, v10, v11
	v_cvt_pk_bf16_f32 v11, v12, v13
	ds_write_b64 v115, v[10:11] offset:18432
	v_cvt_pk_bf16_f32 v10, v22, v23
	v_cvt_pk_bf16_f32 v11, v24, v25
	ds_write_b64 v116, v[10:11] offset:18432
	ds_read_b64_tr_b16 v[12:13], v112 offset:37440
	ds_read_b64_tr_b16 v[10:11], v112 offset:36864
	ds_read_b64_tr_b16 v[24:25], v112 offset:37472
	ds_read_b64_tr_b16 v[22:23], v112 offset:36896
	s_waitcnt lgkmcnt(9)
	v_mfma_f32_16x16x32_bf16 v[34:37], v[34:37], v[14:17], 0
	s_waitcnt lgkmcnt(7)
	v_mfma_f32_16x16x32_bf16 v[14:17], v[26:29], v[14:17], 0
	ds_read_b64_tr_b16 v[26:27], v112 offset:41472
	ds_read_b64_tr_b16 v[28:29], v112 offset:42048
	ds_read_b64_tr_b16 v[44:45], v112 offset:42080
	ds_read_b64_tr_b16 v[42:43], v112 offset:41504
	s_waitcnt lgkmcnt(6)
	v_mfma_f32_16x16x32_bf16 v[10:13], v[10:13], v[2:5], 0
	s_waitcnt lgkmcnt(4)
	v_mfma_f32_16x16x32_bf16 v[22:25], v[22:25], v[2:5], 0
	s_waitcnt lgkmcnt(2)
	v_mfma_f32_16x16x32_bf16 v[10:13], v[26:29], v[6:9], v[10:13]
	s_waitcnt lgkmcnt(0)
	v_mfma_f32_16x16x32_bf16 v[22:25], v[42:45], v[6:9], v[22:25]
	s_nop 5
	ds_write_b128 v123, v[10:13]
	s_nop 0
	ds_write_b128 v124, v[22:25]
	s_waitcnt lgkmcnt(0)
	s_barrier
	ds_read_b64_tr_b16 v[12:13], v122 offset:576
	ds_read_b64_tr_b16 v[10:11], v122
	v_mfma_f32_16x16x32_bf16 v[22:25], v[38:41], v[18:21], v[34:37]
	ds_read_b128 v[26:29], v125 offset:18432
	s_nop 1
	ds_read_b64_tr_b16 v[36:37], v122 offset:608
	ds_read_b64_tr_b16 v[34:35], v122 offset:32
	v_cndmask_b32_e64 v38, v104, v103, s[0:1]
	v_mfma_f32_16x16x32_bf16 v[14:17], v[30:33], v[18:21], v[14:17]
	ds_read_b128 v[18:21], v125 offset:18496
	ds_read_b64_tr_b16 v[30:31], v122 offset:4608
	ds_read_b64_tr_b16 v[32:33], v122 offset:5184
	s_waitcnt lgkmcnt(5)
	v_mfma_f32_16x16x32_bf16 v[10:13], v[10:13], v[26:29], v[22:25]
	s_nop 2
	ds_read_b64_tr_b16 v[24:25], v122 offset:5216
	ds_read_b64_tr_b16 v[22:23], v122 offset:4640
	s_waitcnt lgkmcnt(5)
	v_mfma_f32_16x16x32_bf16 v[14:17], v[34:37], v[26:29], v[14:17]
	v_add_u32_e32 v26, s30, v38
	v_ashrrev_i32_e32 v27, 31, v26
	v_lshlrev_b64 v[26:27], 10, v[26:27]
	s_waitcnt lgkmcnt(2)
	v_mfma_f32_16x16x32_bf16 v[10:13], v[30:33], v[18:21], v[10:13]
	v_lshl_add_u64 v[26:27], s[4:5], 0, v[26:27]
	v_lshl_add_u64 v[26:27], v[26:27], 0, s[10:11]
	v_lshl_add_u64 v[26:27], v[26:27], 0, s[26:27]
	s_waitcnt lgkmcnt(0)
	v_mfma_f32_16x16x32_bf16 v[14:17], v[22:25], v[18:21], v[14:17]
	s_nop 2
	v_cvt_pk_bf16_f32 v172, v10, v11
	v_cvt_pk_bf16_f32 v173, v12, v13
	v_lshl_add_u64 v[12:13], v[26:27], 0, s[24:25]
	v_lshl_add_u64 v[12:13], v[170:171], 1, v[12:13]
	s_nop 0
	v_cvt_pk_bf16_f32 v174, v14, v15
	v_cvt_pk_bf16_f32 v175, v16, v17
	s_nop 1
	v_permlane16_swap_b32_e32 v172, v174
	v_permlane16_swap_b32_e32 v173, v175
	global_store_dwordx4 v[12:13], v[172:175], off sc1
	s_cbranch_scc0 .LBB0_239

.LBB0_233:
	ds_read_b64_tr_b16 v[134:135], v117 offset:576
	ds_read_b64_tr_b16 v[132:133], v117
	ds_read_b128 v[136:139], v125 offset:18432
	ds_read_b64_tr_b16 v[142:143], v117 offset:608
	ds_read_b64_tr_b16 v[140:141], v117 offset:32
	ds_read_b128 v[144:147], v125 offset:18496
	ds_read_b64_tr_b16 v[150:151], v117 offset:4608
	ds_read_b64_tr_b16 v[152:153], v117 offset:5184
	ds_read_b64_tr_b16 v[156:157], v117 offset:5216
	ds_read_b64_tr_b16 v[154:155], v117 offset:4640
	s_waitcnt lgkmcnt(7)
	v_mfma_f32_16x16x32_bf16 v[50:53], v[132:135], v[136:139], v[50:53]
	ds_read_b64_tr_b16 v[158:159], v101 offset:55296
	ds_read_b64_tr_b16 v[160:161], v101 offset:55872
	v_add_u32_e32 v131, v94, v97
	s_waitcnt lgkmcnt(7)
	v_mfma_f32_16x16x32_bf16 v[136:139], v[140:143], v[136:139], v[54:57]
	s_waitcnt lgkmcnt(4)
	v_mfma_f32_16x16x32_bf16 v[50:53], v[150:153], v[144:147], v[50:53]
	s_nop 0
	v_add_u32_e32 v56, s29, v71
	v_add_u32_e32 v54, 64, v129
	v_cndmask_b32_e64 v54, v54, v56, s[0:1]
	s_waitcnt lgkmcnt(2)
	v_mfma_f32_16x16x32_bf16 v[136:139], v[154:157], v[144:147], v[136:139]
	ds_read_b64_tr_b16 v[144:145], v101 offset:59904
	ds_read_b64_tr_b16 v[146:147], v101 offset:60480
	v_add_u32_e32 v54, s30, v54
	v_ashrrev_i32_e32 v55, 31, v54
	s_waitcnt lgkmcnt(2)
	v_mfma_f32_16x16x32_bf16 v[46:49], v[158:161], v[132:135], v[46:49]
	v_cvt_pk_bf16_f32 v172, v50, v51
	v_cvt_pk_bf16_f32 v173, v52, v53
	ds_read_b128 v[50:53], v118 offset:46080
	v_mfma_f32_16x16x32_bf16 v[42:45], v[158:161], v[140:143], v[42:45]
	v_lshlrev_b64 v[54:55], 10, v[54:55]
	v_lshl_add_u64 v[54:55], v[80:81], 0, v[54:55]
	s_nop 0
	s_waitcnt lgkmcnt(1)
	v_mfma_f32_16x16x32_bf16 v[46:49], v[144:147], v[150:153], v[46:49]
	v_cvt_pk_bf16_f32 v174, v136, v137
	v_cvt_pk_bf16_f32 v175, v138, v139
	s_nop 1
	v_permlane16_swap_b32_e32 v172, v174
	v_permlane16_swap_b32_e32 v173, v175
	global_store_dwordx4 v[54:55], v[172:175], off sc1
	v_mfma_f32_16x16x32_bf16 v[42:45], v[144:147], v[154:157], v[42:45]
	s_waitcnt vmcnt(8)
	v_lshlrev_b32_e32 v136, 16, v22
	s_waitcnt lgkmcnt(0)
	s_nop 0
	v_pk_mul_f32 v[48:49], v[52:53], v[48:49]
	v_pk_mul_f32 v[46:47], v[50:51], v[46:47]
	v_and_b32_e32 v137, 0xffff0000, v22
	v_lshlrev_b32_e32 v22, 16, v23
	v_pk_mul_f32 v[44:45], v[52:53], v[44:45]
	v_pk_mul_f32 v[42:43], v[50:51], v[42:43]
	v_cvt_pk_bf16_f32 v50, v46, v47
	v_cvt_pk_bf16_f32 v51, v48, v49
	ds_write_b64 v131, v[50:51] offset:27648
	v_cvt_pk_bf16_f32 v50, v42, v43
	v_cvt_pk_bf16_f32 v51, v44, v45
	ds_write_b64 v119, v[50:51] offset:27648
	ds_read_b128 v[50:53], v120
	ds_read_b128 v[132:135], v120 offset:16
	v_and_b32_e32 v23, 0xffff0000, v23
	v_lshlrev_b32_e32 v138, 16, v24
	v_and_b32_e32 v139, 0xffff0000, v24
	s_waitcnt lgkmcnt(1)
	v_exp_f32_e64 v54, -v50
	v_exp_f32_e64 v55, -v51
	v_exp_f32_e32 v50, v50
	v_exp_f32_e32 v51, v51
	s_waitcnt lgkmcnt(0)
	v_exp_f32_e32 v24, v134
	v_pk_mul_f32 v[54:55], v[54:55], v[136:137]
	s_waitcnt vmcnt(6)
	v_lshlrev_b32_e32 v136, 16, v18
	v_and_b32_e32 v137, 0xffff0000, v18
	v_pk_mul_f32 v[136:137], v[50:51], v[136:137]
	s_nop 0
	v_cvt_pk_bf16_f32 v18, v136, v137
	v_cvt_pk_bf16_f32 v136, v54, v55
	v_exp_f32_e64 v54, -v52
	v_exp_f32_e64 v55, -v53
	v_exp_f32_e32 v52, v52
	v_exp_f32_e32 v53, v53
	v_pk_mul_f32 v[22:23], v[54:55], v[22:23]
	v_lshlrev_b32_e32 v54, 16, v19
	v_and_b32_e32 v55, 0xffff0000, v19
	v_pk_mul_f32 v[54:55], v[52:53], v[54:55]
	v_cvt_pk_bf16_f32 v137, v22, v23
	v_cvt_pk_bf16_f32 v19, v54, v55
	v_exp_f32_e64 v54, -v132
	v_exp_f32_e64 v55, -v133
	v_exp_f32_e32 v22, v132
	v_exp_f32_e32 v23, v133
	v_lshlrev_b32_e32 v132, 16, v20
	v_pk_mul_f32 v[54:55], v[54:55], v[138:139]
	v_and_b32_e32 v133, 0xffff0000, v20
	v_pk_mul_f32 v[132:133], v[22:23], v[132:133]
	v_cvt_pk_bf16_f32 v138, v54, v55
	v_exp_f32_e64 v54, -v134
	v_exp_f32_e64 v55, -v135
	v_cvt_pk_bf16_f32 v20, v132, v133
	v_lshlrev_b32_e32 v132, 16, v25
	v_and_b32_e32 v133, 0xffff0000, v25
	v_exp_f32_e32 v25, v135
	v_pk_mul_f32 v[54:55], v[54:55], v[132:133]
	v_lshlrev_b32_e32 v132, 16, v21
	v_and_b32_e32 v133, 0xffff0000, v21
	v_pk_mul_f32 v[132:133], v[24:25], v[132:133]
	v_cvt_pk_bf16_f32 v139, v54, v55
	v_cvt_pk_bf16_f32 v21, v132, v133
	ds_write_b128 v111, v[18:21]
	ds_write_b128 v111, v[136:139] offset:64512
	s_and_saveexec_b64 s[26:27], vcc
	s_cbranch_execz .LBB0_235
	ds_write_b128 v126, v[50:53] offset:46336
	ds_write_b128 v126, v[22:25] offset:46352
.LBB0_235:
	s_or_b64 exec, exec, s[26:27]
	ds_write_b128 v121, v[10:13]
	s_waitcnt vmcnt(5)
	ds_write_b128 v111, v[14:17] offset:36864
	v_add_u32_e32 v10, s29, v90
	v_cndmask_b32_e64 v10, v130, v10, s[0:1]
	v_ashrrev_i32_e32 v11, 31, v10
	s_add_i32 s31, s31, 2
	v_lshlrev_b64 v[10:11], 7, v[10:11]
	s_min_u32 s26, s31, 60
	v_lshl_add_u64 v[12:13], v[72:73], 0, v[10:11]
	v_lshl_add_u64 v[14:15], v[76:77], 0, v[10:11]
	global_load_dwordx4 v[18:21], v[12:13], off
	global_load_dwordx4 v[22:25], v[14:15], off
	v_lshl_add_u32 v12, s26, 6, v90
	v_sub_u32_e32 v13, 0xfff, v12
	v_cndmask_b32_e64 v12, v13, v12, s[0:1]
	v_ashrrev_i32_e32 v13, 31, v12
	v_lshlrev_b64 v[54:55], 7, v[12:13]
	v_lshl_add_u64 v[10:11], v[78:79], 0, v[10:11]
	v_lshl_add_u64 v[14:15], v[74:75], 0, v[54:55]
	global_load_dwordx4 v[10:13], v[10:11], off
	s_nop 0
	global_load_dwordx4 v[14:17], v[14:15], off
	s_waitcnt lgkmcnt(0)
	s_barrier
	ds_read_b128 v[50:53], v95 offset:64512
	ds_read_b128 v[132:135], v125
	ds_read_b128 v[136:139], v125 offset:64
	ds_read_b128 v[140:143], v95 offset:64576
	ds_read_b128 v[144:147], v102 offset:2304
	ds_read_b128 v[150:153], v102 offset:2368
	s_waitcnt lgkmcnt(4)
	v_mfma_f32_16x16x32_bf16 v[50:53], v[50:53], v[132:135], 0
	ds_read_b128 v[154:157], v95 offset:27648
	ds_read_b128 v[158:161], v95 offset:27712
	ds_read_b128 v[162:165], v95 offset:29952
	ds_read_b128 v[166:169], v95 offset:30016
	s_waitcnt lgkmcnt(5)
	v_mfma_f32_16x16x32_bf16 v[144:147], v[144:147], v[132:135], 0
	v_mfma_f32_16x16x32_bf16 v[50:53], v[140:143], v[136:139], v[50:53]
	s_waitcnt lgkmcnt(4)
	v_mfma_f32_16x16x32_bf16 v[140:143], v[150:153], v[136:139], v[144:147]
	s_waitcnt lgkmcnt(3)
	v_mfma_f32_16x16x32_bf16 v[154:157], v[154:157], v[132:135], 0
	s_nop 3
	v_mul_f32_e64 v52, v60, v52
	v_mul_f32_e64 v53, v61, v53
	v_pk_mul_f32 v[50:51], v[58:59], v[50:51]
	v_pk_mul_f32 v[142:143], v[64:65], v[142:143]
	s_waitcnt lgkmcnt(1)
	v_mfma_f32_16x16x32_bf16 v[132:135], v[162:165], v[132:135], 0
	v_mul_f32_e64 v140, v62, v140
	v_mul_f32_e64 v141, v63, v141
	v_cvt_pk_bf16_f32 v50, v50, v51
	v_cvt_pk_bf16_f32 v51, v52, v53
	ds_write_b64 v115, v[50:51] offset:18432
	v_cvt_pk_bf16_f32 v50, v140, v141
	v_cvt_pk_bf16_f32 v51, v142, v143
	ds_write_b64 v116, v[50:51] offset:18432
	ds_read_b64_tr_b16 v[52:53], v112 offset:37440
	ds_read_b64_tr_b16 v[50:51], v112 offset:36864
	v_mfma_f32_16x16x32_bf16 v[144:147], v[158:161], v[136:139], v[154:157]
	s_waitcnt lgkmcnt(4)
	v_mfma_f32_16x16x32_bf16 v[132:135], v[166:169], v[136:139], v[132:135]
	ds_read_b64_tr_b16 v[138:139], v112 offset:37472
	ds_read_b64_tr_b16 v[136:137], v112 offset:36896
	ds_read_b64_tr_b16 v[140:141], v112 offset:41472
	ds_read_b64_tr_b16 v[142:143], v112 offset:42048
	ds_read_b64_tr_b16 v[152:153], v112 offset:42080
	ds_read_b64_tr_b16 v[150:151], v112 offset:41504
	s_waitcnt lgkmcnt(6)
	v_mfma_f32_16x16x32_bf16 v[50:53], v[50:53], v[2:5], 0
	s_waitcnt lgkmcnt(4)
	v_mfma_f32_16x16x32_bf16 v[136:139], v[136:139], v[2:5], 0
	s_waitcnt lgkmcnt(2)
	v_mfma_f32_16x16x32_bf16 v[50:53], v[140:143], v[6:9], v[50:53]
	s_waitcnt lgkmcnt(0)
	v_mfma_f32_16x16x32_bf16 v[136:139], v[150:153], v[6:9], v[136:139]
	s_nop 5
	ds_write_b128 v123, v[50:53]
	s_nop 0
	ds_write_b128 v124, v[136:139]
	s_waitcnt lgkmcnt(0)
	s_barrier
	ds_read_b64_tr_b16 v[50:51], v122
	ds_read_b64_tr_b16 v[52:53], v122 offset:576
	ds_read_b64_tr_b16 v[138:139], v122 offset:608
	ds_read_b64_tr_b16 v[140:141], v122 offset:4608
	ds_read_b64_tr_b16 v[136:137], v122 offset:32
	ds_read_b128 v[150:153], v125 offset:18432
	ds_read_b128 v[154:157], v125 offset:18496
	ds_read_b128 v[158:161], v118 offset:46336
	ds_read_b64_tr_b16 v[142:143], v122 offset:5184
	s_waitcnt lgkmcnt(3)
	v_mfma_f32_16x16x32_bf16 v[144:147], v[50:53], v[150:153], v[144:147]
	v_mfma_f32_16x16x32_bf16 v[132:135], v[136:139], v[150:153], v[132:135]
	ds_read_b64_tr_b16 v[152:153], v122 offset:5216
	ds_read_b64_tr_b16 v[150:151], v122 offset:4640
	s_waitcnt lgkmcnt(2)
	v_mfma_f32_16x16x32_bf16 v[144:147], v[140:143], v[154:157], v[144:147]
	s_waitcnt lgkmcnt(0)
	v_mfma_f32_16x16x32_bf16 v[132:135], v[150:153], v[154:157], v[132:135]
	ds_read_b64_tr_b16 v[154:155], v101 offset:64512
	ds_read_b64_tr_b16 v[156:157], v101 offset:65088
	ds_read_b64_tr_b16 v[162:163], v105 offset:4608
	ds_read_b64_tr_b16 v[164:165], v105 offset:5184
	s_waitcnt lgkmcnt(2)
	v_mfma_f32_16x16x32_bf16 v[46:49], v[154:157], v[50:53], v[46:49]
	v_add_u32_e32 v50, 64, v56
	v_cndmask_b32_e64 v50, v129, v50, s[0:1]
	v_add_u32_e32 v50, s30, v50
	v_mfma_f32_16x16x32_bf16 v[42:45], v[154:157], v[136:139], v[42:45]
	v_ashrrev_i32_e32 v51, 31, v50
	v_lshlrev_b64 v[50:51], 10, v[50:51]
	v_lshl_add_u64 v[56:57], v[80:81], 0, v[50:51]
	s_waitcnt lgkmcnt(0)
	v_mfma_f32_16x16x32_bf16 v[46:49], v[162:165], v[140:143], v[46:49]
	v_cvt_pk_bf16_f32 v172, v144, v145
	v_cvt_pk_bf16_f32 v173, v146, v147
	s_nop 0
	v_mfma_f32_16x16x32_bf16 v[42:45], v[162:165], v[150:153], v[42:45]
	v_cvt_pk_bf16_f32 v174, v132, v133
	s_nop 2
	v_pk_mul_f32 v[48:49], v[160:161], v[48:49]
	v_pk_mul_f32 v[46:47], v[158:159], v[46:47]
	v_cvt_pk_bf16_f32 v51, v48, v49
	v_cvt_pk_bf16_f32 v50, v46, v47
	v_pk_mul_f32 v[44:45], v[160:161], v[44:45]
	v_pk_mul_f32 v[42:43], v[158:159], v[42:43]
	ds_write_b64 v131, v[50:51] offset:27648
	v_cvt_pk_bf16_f32 v50, v42, v43
	v_cvt_pk_bf16_f32 v51, v44, v45
	ds_write_b64 v119, v[50:51] offset:27648
	ds_read_b128 v[50:53], v113
	v_cvt_pk_bf16_f32 v175, v134, v135
	s_nop 1
	v_permlane16_swap_b32_e32 v172, v174
	v_permlane16_swap_b32_e32 v173, v175
	global_store_dwordx4 v[56:57], v[172:175], off sc1
	ds_read_b128 v[132:135], v113 offset:16
	s_waitcnt vmcnt(8)
	v_lshlrev_b32_e32 v136, 16, v38
	s_waitcnt lgkmcnt(1)
	v_exp_f32_e64 v56, -v50
	v_exp_f32_e64 v57, -v51
	v_exp_f32_e32 v50, v50
	v_exp_f32_e32 v51, v51
	v_and_b32_e32 v137, 0xffff0000, v38
	v_pk_mul_f32 v[56:57], v[56:57], v[136:137]
	v_lshlrev_b32_e32 v136, 16, v34
	v_and_b32_e32 v137, 0xffff0000, v34
	v_pk_mul_f32 v[136:137], v[50:51], v[136:137]
	v_lshlrev_b32_e32 v38, 16, v39
	v_cvt_pk_bf16_f32 v34, v136, v137
	v_cvt_pk_bf16_f32 v136, v56, v57
	v_exp_f32_e64 v56, -v52
	v_exp_f32_e64 v57, -v53
	v_exp_f32_e32 v52, v52
	v_exp_f32_e32 v53, v53
	v_and_b32_e32 v39, 0xffff0000, v39
	v_pk_mul_f32 v[38:39], v[56:57], v[38:39]
	v_lshlrev_b32_e32 v56, 16, v35
	v_and_b32_e32 v57, 0xffff0000, v35
	v_pk_mul_f32 v[56:57], v[52:53], v[56:57]
	v_cvt_pk_bf16_f32 v137, v38, v39
	v_cvt_pk_bf16_f32 v35, v56, v57
	s_waitcnt lgkmcnt(0)
	v_exp_f32_e64 v56, -v132
	v_exp_f32_e64 v57, -v133
	v_exp_f32_e32 v38, v132
	v_exp_f32_e32 v39, v133
	v_lshlrev_b32_e32 v138, 16, v40
	v_and_b32_e32 v139, 0xffff0000, v40
	v_pk_mul_f32 v[56:57], v[56:57], v[138:139]
	v_lshlrev_b32_e32 v132, 16, v36
	v_and_b32_e32 v133, 0xffff0000, v36
	v_pk_mul_f32 v[132:133], v[38:39], v[132:133]
	v_cvt_pk_bf16_f32 v138, v56, v57
	v_exp_f32_e64 v56, -v134
	v_exp_f32_e64 v57, -v135
	v_cvt_pk_bf16_f32 v36, v132, v133
	v_lshlrev_b32_e32 v132, 16, v41
	v_and_b32_e32 v133, 0xffff0000, v41
	v_exp_f32_e32 v40, v134
	v_exp_f32_e32 v41, v135
	v_pk_mul_f32 v[56:57], v[56:57], v[132:133]
	v_lshlrev_b32_e32 v132, 16, v37
	v_and_b32_e32 v133, 0xffff0000, v37
	v_pk_mul_f32 v[132:133], v[40:41], v[132:133]
	v_cvt_pk_bf16_f32 v139, v56, v57
	v_cvt_pk_bf16_f32 v37, v132, v133
	ds_write_b128 v111, v[34:37]
	ds_write_b128 v111, v[136:139] offset:55296
	s_and_saveexec_b64 s[26:27], vcc
	s_cbranch_execz .LBB0_232
	ds_write_b128 v126, v[50:53] offset:46080
	ds_write_b128 v126, v[38:41] offset:46096
	s_branch .LBB0_232
.LBB0_237:
	s_waitcnt vmcnt(1)
	ds_read_b64_tr_b16 v[28:29], v117 offset:576
	ds_read_b64_tr_b16 v[26:27], v117
	s_waitcnt vmcnt(0)
	ds_read_b64_tr_b16 v[32:33], v117 offset:608
	ds_read_b64_tr_b16 v[30:31], v117 offset:32
	ds_read_b128 v[34:37], v125 offset:18432
	ds_read_b128 v[38:41], v125 offset:18496
	v_cndmask_b32_e64 v76, v100, v99, s[0:1]
	ds_read_b64_tr_b16 v[72:73], v117 offset:4608
	ds_read_b64_tr_b16 v[74:75], v117 offset:5184
	v_add_u32_e32 v80, s30, v76
	ds_read_b64_tr_b16 v[78:79], v117 offset:5216
	ds_read_b64_tr_b16 v[76:77], v117 offset:4640
	s_waitcnt lgkmcnt(5)
	v_mfma_f32_16x16x32_bf16 v[50:53], v[26:29], v[34:37], v[50:53]
	v_ashrrev_i32_e32 v81, 31, v80
	v_lshlrev_b64 v[80:81], 10, v[80:81]
	v_lshl_add_u64 v[80:81], s[4:5], 0, v[80:81]
	v_mfma_f32_16x16x32_bf16 v[34:37], v[30:33], v[34:37], v[54:57]
	s_nop 2
	ds_read_b64_tr_b16 v[54:55], v101 offset:55296
	ds_read_b64_tr_b16 v[56:57], v101 offset:55872
	s_lshl_b32 s10, s10, 1
	v_lshl_add_u64 v[80:81], v[80:81], 0, s[10:11]
	s_waitcnt lgkmcnt(4)
	v_mfma_f32_16x16x32_bf16 v[50:53], v[72:75], v[38:41], v[50:53]
	s_lshl_b32 s26, s28, 1
	s_mov_b32 s27, s11
	s_waitcnt lgkmcnt(2)
	v_mfma_f32_16x16x32_bf16 v[34:37], v[76:79], v[38:41], v[34:37]
	ds_read_b64_tr_b16 v[38:39], v101 offset:59904
	ds_read_b64_tr_b16 v[40:41], v101 offset:60480
	s_waitcnt lgkmcnt(2)
	v_mfma_f32_16x16x32_bf16 v[26:29], v[54:57], v[26:29], v[46:49]
	v_mfma_f32_16x16x32_bf16 v[30:33], v[54:57], v[30:33], v[42:45]
	s_nop 1
	v_lshl_add_u64 v[46:47], v[80:81], 0, s[26:27]
	v_lshl_add_u64 v[46:47], v[46:47], 0, s[24:25]
	v_lshl_add_u64 v[46:47], v[170:171], 1, v[46:47]
	ds_read_b128 v[42:45], v118 offset:46080
	s_waitcnt lgkmcnt(1)
	v_mfma_f32_16x16x32_bf16 v[26:29], v[38:41], v[72:75], v[26:29]
	v_cvt_pk_bf16_f32 v172, v50, v51
	v_cvt_pk_bf16_f32 v173, v52, v53
	s_nop 0
	v_mfma_f32_16x16x32_bf16 v[30:33], v[38:41], v[76:79], v[30:33]
	v_lshlrev_b32_e32 v38, 16, v24
	s_waitcnt lgkmcnt(0)
	s_nop 1
	v_pk_mul_f32 v[28:29], v[44:45], v[28:29]
	v_pk_mul_f32 v[26:27], v[42:43], v[26:27]
	v_and_b32_e32 v39, 0xffff0000, v24
	v_cvt_pk_bf16_f32 v26, v26, v27
	v_pk_mul_f32 v[32:33], v[44:45], v[32:33]
	v_pk_mul_f32 v[30:31], v[42:43], v[30:31]
	v_cvt_pk_bf16_f32 v27, v28, v29
	ds_write_b64 v131, v[26:27] offset:27648
	v_cvt_pk_bf16_f32 v26, v30, v31
	v_cvt_pk_bf16_f32 v27, v32, v33
	ds_write_b64 v119, v[26:27] offset:27648
	ds_read_b128 v[26:29], v120
	v_cvt_pk_bf16_f32 v174, v34, v35
	v_cvt_pk_bf16_f32 v175, v36, v37
	s_nop 1
	v_permlane16_swap_b32_e32 v172, v174
	v_permlane16_swap_b32_e32 v173, v175
	global_store_dwordx4 v[46:47], v[172:175], off sc1
	ds_read_b128 v[30:33], v120 offset:16
	s_waitcnt lgkmcnt(1)
	v_exp_f32_e64 v34, -v26
	v_exp_f32_e64 v35, -v27
	v_exp_f32_e32 v26, v26
	v_exp_f32_e32 v27, v27
	v_lshlrev_b32_e32 v36, 16, v22
	v_and_b32_e32 v37, 0xffff0000, v22
	v_pk_mul_f32 v[34:35], v[34:35], v[36:37]
	v_lshlrev_b32_e32 v36, 16, v18
	v_and_b32_e32 v37, 0xffff0000, v18
	v_pk_mul_f32 v[36:37], v[26:27], v[36:37]
	v_lshlrev_b32_e32 v22, 16, v23
	v_cvt_pk_bf16_f32 v18, v36, v37
	v_exp_f32_e64 v36, -v28
	v_exp_f32_e64 v37, -v29
	v_exp_f32_e32 v28, v28
	v_exp_f32_e32 v29, v29
	v_and_b32_e32 v23, 0xffff0000, v23
	v_pk_mul_f32 v[22:23], v[36:37], v[22:23]
	v_lshlrev_b32_e32 v36, 16, v19
	v_and_b32_e32 v37, 0xffff0000, v19
	v_pk_mul_f32 v[36:37], v[28:29], v[36:37]
	v_cvt_pk_bf16_f32 v34, v34, v35
	v_cvt_pk_bf16_f32 v19, v36, v37
	s_waitcnt lgkmcnt(0)
	v_exp_f32_e64 v36, -v30
	v_exp_f32_e64 v37, -v31
	v_cvt_pk_bf16_f32 v35, v22, v23
	v_exp_f32_e32 v22, v30
	v_exp_f32_e32 v23, v31
	v_pk_mul_f32 v[30:31], v[36:37], v[38:39]
	v_lshlrev_b32_e32 v36, 16, v20
	v_and_b32_e32 v37, 0xffff0000, v20
	v_pk_mul_f32 v[36:37], v[22:23], v[36:37]
	v_lshlrev_b32_e32 v38, 16, v25
	v_and_b32_e32 v39, 0xffff0000, v25
	v_exp_f32_e32 v24, v32
	v_exp_f32_e32 v25, v33
	v_cvt_pk_bf16_f32 v20, v36, v37
	v_cvt_pk_bf16_f32 v36, v30, v31
	v_exp_f32_e64 v30, -v32
	v_exp_f32_e64 v31, -v33
	v_lshlrev_b32_e32 v32, 16, v21
	v_and_b32_e32 v33, 0xffff0000, v21
	v_pk_mul_f32 v[32:33], v[24:25], v[32:33]
	v_pk_mul_f32 v[30:31], v[30:31], v[38:39]
	v_cvt_pk_bf16_f32 v21, v32, v33
	v_cvt_pk_bf16_f32 v37, v30, v31
	ds_write_b128 v111, v[18:21]
	ds_write_b128 v111, v[34:37] offset:64512
	s_and_saveexec_b64 s[28:29], vcc
	s_cbranch_execz .LBB0_222
	ds_write_b128 v126, v[26:29] offset:46336
	ds_write_b128 v126, v[22:25] offset:46352
	s_branch .LBB0_222
